# P1 side job (cached latent rows to bf16 on the 120 workgroups without a third GEMM unit): 16-chunk pass in front of the 8-chunk loop, twice the bytes in flight
# speedup vs baseline: 1.0121x; 1.0121x over previous
.LBB0_577:
	s_cmpk_lg_i32 s59, 0x100
	s_cselect_b64 s[0:1], -1, 0
	s_cmpk_lt_u32 s96, 0x88
	s_cselect_b64 s[2:3], -1, 0
	s_or_b64 s[0:1], s[2:3], s[0:1]
	v_readlane_b32 s62, v245, 37
	s_and_b64 vcc, exec, s[0:1]
	v_readlane_b32 s63, v245, 38
	s_cbranch_vccnz .LBB0_593
	s_add_i32 s6, s96, 0xffffff78
	s_ashr_i32 s7, s6, 31
	s_lshl_b64 s[0:1], s[6:7], 9
	v_or_b32_e32 v2, s0, v0
	v_mov_b32_e32 v3, s1
	s_mov_b64 s[0:1], 0x69000
	v_lshl_add_u64 v[6:7], v[2:3], 0, s[0:1]
	s_mov_b64 s[0:1], 0x800000
	v_mov_b32_e32 v13, 0
	v_cmp_gt_u64_e32 vcc, s[0:1], v[6:7]
	v_lshlrev_b32_e32 v4, 3, v0
	v_mov_b64_e32 v[8:9], v[2:3]
	s_and_saveexec_b64 s[8:9], vcc
	s_cbranch_execz .LBB0_582
	s_load_dwordx16 s[12:27], s[62:63], 0x0
	s_lshl_b64 s[0:1], s[6:7], 13
	v_lshlrev_b32_e32 v12, 4, v0
	v_mov_b32_e32 v5, v13
	s_mov_b64 s[10:11], 0
	s_waitcnt lgkmcnt(0)
	s_add_u32 s0, s22, s0
	s_addc_u32 s1, s23, s1
	v_lshl_add_u64 v[10:11], s[0:1], 0, v[12:13]
	s_lshl_b64 s[0:1], s[6:7], 12
	s_add_u32 s0, s34, s0
	s_addc_u32 s1, s35, s1
	v_lshl_add_u64 v[8:9], s[0:1], 0, v[4:5]
	s_mov_b64 s[0:1], 0x16d00000
	v_lshl_add_u64 v[12:13], v[8:9], 0, s[0:1]
	s_mov_b32 s0, 0xf0000
	s_mov_b32 s1, 0x1e0000
	s_mov_b32 s2, 0x2d0000
	s_mov_b32 s3, 0x78000
	s_mov_b32 s4, 0x168000
	s_mov_b32 s5, 0x258000
	s_mov_b64 s[12:13], 0x78000
	s_mov_b64 s[14:15], 0x780000
	s_mov_b64 s[18:19], 0x3c0000
	s_mov_b64 s[20:21], 0xe1000
	s_mov_b64 s[24:25], 0x7fffff
	v_mov_b64_e32 v[8:9], v[2:3]
	s_mov_b64 s[42:43], 0xf0000
	s_mov_b64 s[44:45], 0x78000
	s_mov_b64 s[46:47], 0xf00000
	s_mov_b64 s[48:49], 0x69000
	s_mov_b64 s[50:51], 0x800000
	s_mov_b64 s[40:41], exec
	v_lshl_add_u64 v[60:61], v[8:9], 0, s[20:21]
	v_cmp_ge_u64_e32 vcc, s[24:25], v[60:61]
	s_and_b64 exec, exec, vcc
	s_cbranch_execz .Lcv16_done
.Lcv16_loop:
	global_load_dwordx4 v[64:67], v[10:11], off nt
	v_lshl_add_u64 v[62:63], v[10:11], 0, s[42:43]
	global_load_dwordx4 v[68:71], v[62:63], off nt
	v_lshl_add_u64 v[62:63], v[62:63], 0, s[42:43]
	global_load_dwordx4 v[72:75], v[62:63], off nt
	v_lshl_add_u64 v[62:63], v[62:63], 0, s[42:43]
	global_load_dwordx4 v[76:79], v[62:63], off nt
	v_lshl_add_u64 v[62:63], v[62:63], 0, s[42:43]
	global_load_dwordx4 v[80:83], v[62:63], off nt
	v_lshl_add_u64 v[62:63], v[62:63], 0, s[42:43]
	global_load_dwordx4 v[84:87], v[62:63], off nt
	v_lshl_add_u64 v[62:63], v[62:63], 0, s[42:43]
	global_load_dwordx4 v[88:91], v[62:63], off nt
	v_lshl_add_u64 v[62:63], v[62:63], 0, s[42:43]
	global_load_dwordx4 v[92:95], v[62:63], off nt
	v_lshl_add_u64 v[62:63], v[62:63], 0, s[42:43]
	global_load_dwordx4 v[96:99], v[62:63], off nt
	v_lshl_add_u64 v[62:63], v[62:63], 0, s[42:43]
	global_load_dwordx4 v[100:103], v[62:63], off nt
	v_lshl_add_u64 v[62:63], v[62:63], 0, s[42:43]
	global_load_dwordx4 v[104:107], v[62:63], off nt
	v_lshl_add_u64 v[62:63], v[62:63], 0, s[42:43]
	global_load_dwordx4 v[108:111], v[62:63], off nt
	v_lshl_add_u64 v[62:63], v[62:63], 0, s[42:43]
	global_load_dwordx4 v[112:115], v[62:63], off nt
	v_lshl_add_u64 v[62:63], v[62:63], 0, s[42:43]
	global_load_dwordx4 v[116:119], v[62:63], off nt
	v_lshl_add_u64 v[62:63], v[62:63], 0, s[42:43]
	global_load_dwordx4 v[120:123], v[62:63], off nt
	v_lshl_add_u64 v[62:63], v[62:63], 0, s[42:43]
	global_load_dwordx4 v[124:127], v[62:63], off nt
	s_waitcnt vmcnt(15)
	v_cvt_pk_bf16_f32 v64, v64, v65
	v_cvt_pk_bf16_f32 v65, v66, v67
	global_store_dwordx2 v[12:13], v[64:65], off
	s_waitcnt vmcnt(15)
	v_cvt_pk_bf16_f32 v68, v68, v69
	v_cvt_pk_bf16_f32 v69, v70, v71
	v_lshl_add_u64 v[62:63], v[12:13], 0, s[44:45]
	global_store_dwordx2 v[62:63], v[68:69], off
	s_waitcnt vmcnt(15)
	v_cvt_pk_bf16_f32 v72, v72, v73
	v_cvt_pk_bf16_f32 v73, v74, v75
	v_lshl_add_u64 v[62:63], v[62:63], 0, s[44:45]
	global_store_dwordx2 v[62:63], v[72:73], off
	s_waitcnt vmcnt(15)
	v_cvt_pk_bf16_f32 v76, v76, v77
	v_cvt_pk_bf16_f32 v77, v78, v79
	v_lshl_add_u64 v[62:63], v[62:63], 0, s[44:45]
	global_store_dwordx2 v[62:63], v[76:77], off
	s_waitcnt vmcnt(15)
	v_cvt_pk_bf16_f32 v80, v80, v81
	v_cvt_pk_bf16_f32 v81, v82, v83
	v_lshl_add_u64 v[62:63], v[62:63], 0, s[44:45]
	global_store_dwordx2 v[62:63], v[80:81], off
	s_waitcnt vmcnt(15)
	v_cvt_pk_bf16_f32 v84, v84, v85
	v_cvt_pk_bf16_f32 v85, v86, v87
	v_lshl_add_u64 v[62:63], v[62:63], 0, s[44:45]
	global_store_dwordx2 v[62:63], v[84:85], off
	s_waitcnt vmcnt(15)
	v_cvt_pk_bf16_f32 v88, v88, v89
	v_cvt_pk_bf16_f32 v89, v90, v91
	v_lshl_add_u64 v[62:63], v[62:63], 0, s[44:45]
	global_store_dwordx2 v[62:63], v[88:89], off
	s_waitcnt vmcnt(15)
	v_cvt_pk_bf16_f32 v92, v92, v93
	v_cvt_pk_bf16_f32 v93, v94, v95
	v_lshl_add_u64 v[62:63], v[62:63], 0, s[44:45]
	global_store_dwordx2 v[62:63], v[92:93], off
	s_waitcnt vmcnt(15)
	v_cvt_pk_bf16_f32 v96, v96, v97
	v_cvt_pk_bf16_f32 v97, v98, v99
	v_lshl_add_u64 v[62:63], v[62:63], 0, s[44:45]
	global_store_dwordx2 v[62:63], v[96:97], off
	s_waitcnt vmcnt(15)
	v_cvt_pk_bf16_f32 v100, v100, v101
	v_cvt_pk_bf16_f32 v101, v102, v103
	v_lshl_add_u64 v[62:63], v[62:63], 0, s[44:45]
	global_store_dwordx2 v[62:63], v[100:101], off
	s_waitcnt vmcnt(15)
	v_cvt_pk_bf16_f32 v104, v104, v105
	v_cvt_pk_bf16_f32 v105, v106, v107
	v_lshl_add_u64 v[62:63], v[62:63], 0, s[44:45]
	global_store_dwordx2 v[62:63], v[104:105], off
	s_waitcnt vmcnt(15)
	v_cvt_pk_bf16_f32 v108, v108, v109
	v_cvt_pk_bf16_f32 v109, v110, v111
	v_lshl_add_u64 v[62:63], v[62:63], 0, s[44:45]
	global_store_dwordx2 v[62:63], v[108:109], off
	s_waitcnt vmcnt(15)
	v_cvt_pk_bf16_f32 v112, v112, v113
	v_cvt_pk_bf16_f32 v113, v114, v115
	v_lshl_add_u64 v[62:63], v[62:63], 0, s[44:45]
	global_store_dwordx2 v[62:63], v[112:113], off
	s_waitcnt vmcnt(15)
	v_cvt_pk_bf16_f32 v116, v116, v117
	v_cvt_pk_bf16_f32 v117, v118, v119
	v_lshl_add_u64 v[62:63], v[62:63], 0, s[44:45]
	global_store_dwordx2 v[62:63], v[116:117], off
	s_waitcnt vmcnt(15)
	v_cvt_pk_bf16_f32 v120, v120, v121
	v_cvt_pk_bf16_f32 v121, v122, v123
	v_lshl_add_u64 v[62:63], v[62:63], 0, s[44:45]
	global_store_dwordx2 v[62:63], v[120:121], off
	s_waitcnt vmcnt(15)
	v_cvt_pk_bf16_f32 v124, v124, v125
	v_cvt_pk_bf16_f32 v125, v126, v127
	v_lshl_add_u64 v[62:63], v[62:63], 0, s[44:45]
	global_store_dwordx2 v[62:63], v[124:125], off
	v_lshl_add_u64 v[10:11], v[10:11], 0, s[46:47]
	v_lshl_add_u64 v[12:13], v[12:13], 0, s[14:15]
	v_lshl_add_u64 v[8:9], v[8:9], 0, s[42:43]
	v_lshl_add_u64 v[60:61], v[8:9], 0, s[20:21]
	v_cmp_ge_u64_e32 vcc, s[24:25], v[60:61]
	s_and_b64 exec, exec, vcc
	s_cbranch_execnz .Lcv16_loop
.Lcv16_done:
	s_mov_b64 exec, s[40:41]
	v_lshl_add_u64 v[60:61], v[8:9], 0, s[48:49]
	v_cmp_gt_u64_e32 vcc, s[50:51], v[60:61]
	s_and_b64 exec, exec, vcc
	s_cbranch_execz .LBB0_582
